# prologue weight-transpose loops: 8 loads per batch issued together into distinct registers with one wait (was 32 serialized round trips per item)
# speedup vs baseline: 1.0183x; 1.0090x over previous
.LBB0_22:
	v_lshl_add_u64 v[40:41], v[22:23], 0, s[26:27]
	global_load_dword v100, v[40:41], off
	v_lshl_add_u64 v[40:41], v[20:21], 0, s[26:27]
	global_load_dword v101, v[40:41], off
	v_lshl_add_u64 v[40:41], v[18:19], 0, s[26:27]
	global_load_dword v102, v[40:41], off
	v_lshl_add_u64 v[40:41], v[16:17], 0, s[26:27]
	global_load_dword v103, v[40:41], off
	v_lshl_add_u64 v[40:41], v[14:15], 0, s[26:27]
	global_load_dword v104, v[40:41], off
	v_lshl_add_u64 v[40:41], v[12:13], 0, s[26:27]
	global_load_dword v105, v[40:41], off
	v_lshl_add_u64 v[40:41], v[10:11], 0, s[26:27]
	global_load_dword v106, v[40:41], off
	v_lshl_add_u64 v[40:41], v[8:9], 0, s[26:27]
	s_add_u32 s26, s26, 0x10000
	s_addc_u32 s27, s27, 0
	s_cmp_lg_u32 s26, 0x40000
	global_load_dword v107, v[40:41], off
	s_waitcnt vmcnt(0)
	ds_write_b32 v38, v100
	ds_write_b32 v38, v101 offset:264
	ds_write_b32 v38, v102 offset:528
	ds_write_b32 v38, v103 offset:792
	ds_write_b32 v38, v104 offset:1056
	ds_write_b32 v38, v105 offset:1320
	ds_write_b32 v38, v106 offset:1584
	ds_write_b32 v38, v107 offset:1848
	v_add_u32_e32 v38, 0x840, v38
	s_cbranch_scc1 .LBB0_22
	s_waitcnt lgkmcnt(0)
	ds_read_b32 v8, v25
	ds_read_b32 v9, v25 offset:132
	ds_read_b32 v10, v25 offset:264
	ds_read_b32 v11, v25 offset:396
	ds_read_b32 v14, v25 offset:528
	ds_read_b32 v15, v25 offset:660
	ds_read_b32 v16, v25 offset:792
	ds_read_b32 v17, v25 offset:924
	s_waitcnt lgkmcnt(7)
	v_bfe_u32 v18, v8, 16, 1
	v_add3_u32 v8, v8, v18, s44
	s_waitcnt lgkmcnt(6)
	v_bfe_u32 v18, v9, 16, 1
	v_lshrrev_b32_e32 v8, 16, v8
	v_add3_u32 v9, v9, v18, s44
	v_and_or_b32 v8, v9, s45, v8
	s_waitcnt lgkmcnt(5)
	v_bfe_u32 v9, v10, 16, 1
	v_add3_u32 v9, v10, v9, s44
	s_waitcnt lgkmcnt(4)
	v_bfe_u32 v10, v11, 16, 1
	v_lshrrev_b32_e32 v9, 16, v9
	v_add3_u32 v10, v11, v10, s44
	v_and_or_b32 v9, v10, s45, v9
	s_waitcnt lgkmcnt(3)
	v_bfe_u32 v10, v14, 16, 1
	v_add3_u32 v10, v14, v10, s44
	s_waitcnt lgkmcnt(2)
	v_bfe_u32 v11, v15, 16, 1
	s_lshl_b64 s[26:27], s[24:25], 21
	v_lshrrev_b32_e32 v10, 16, v10
	v_add3_u32 v11, v15, v11, s44
	s_add_u32 s26, s42, s26
	v_and_or_b32 v10, v11, s45, v10
	s_waitcnt lgkmcnt(1)
	v_bfe_u32 v11, v16, 16, 1
	s_addc_u32 s27, s43, s27
	s_lshl_b32 s31, s31, 1
	v_add3_u32 v11, v16, v11, s44
	s_waitcnt lgkmcnt(0)
	v_bfe_u32 v14, v17, 16, 1
	s_add_u32 s26, s26, s31
	v_lshrrev_b32_e32 v11, 16, v11
	v_add3_u32 v14, v17, v14, s44
	s_addc_u32 s27, s27, 0
	v_and_or_b32 v11, v14, s45, v11
	v_or_b32_e32 v14, s29, v24
	v_lshl_add_u64 v[12:13], s[26:27], 0, v[4:5]
	v_lshlrev_b32_e32 v14, 11, v14
	v_mov_b32_e32 v15, v5
	v_lshl_add_u64 v[14:15], v[12:13], 0, v[14:15]
	flat_store_dwordx4 v[14:15], v[8:11]
	ds_read_b32 v8, v25 offset:32
	ds_read_b32 v9, v25 offset:164
	ds_read_b32 v10, v25 offset:296
	ds_read_b32 v11, v25 offset:428
	ds_read_b32 v14, v25 offset:560
	ds_read_b32 v15, v25 offset:692
	ds_read_b32 v16, v25 offset:824
	ds_read_b32 v17, v25 offset:956
	s_waitcnt lgkmcnt(0)
	v_bfe_u32 v18, v8, 16, 1
	v_add3_u32 v8, v8, v18, s44
	v_bfe_u32 v18, v9, 16, 1
	v_lshrrev_b32_e32 v8, 16, v8
	v_add3_u32 v9, v9, v18, s44
	v_and_or_b32 v8, v9, s45, v8
	v_bfe_u32 v9, v10, 16, 1
	v_add3_u32 v9, v10, v9, s44
	v_bfe_u32 v10, v11, 16, 1
	v_lshrrev_b32_e32 v9, 16, v9
	v_add3_u32 v10, v11, v10, s44
	v_and_or_b32 v9, v10, s45, v9
	v_bfe_u32 v10, v14, 16, 1
	v_add3_u32 v10, v14, v10, s44
	v_bfe_u32 v11, v15, 16, 1
	v_lshrrev_b32_e32 v10, 16, v10
	v_add3_u32 v11, v15, v11, s44
	v_and_or_b32 v10, v11, s45, v10
	v_bfe_u32 v11, v16, 16, 1
	v_add3_u32 v11, v16, v11, s44
	v_bfe_u32 v14, v17, 16, 1
	v_lshrrev_b32_e32 v11, 16, v11
	v_add3_u32 v14, v17, v14, s44
	v_and_or_b32 v11, v14, s45, v11
	v_or_b32_e32 v14, s29, v26
	v_lshlrev_b32_e32 v14, 11, v14
	v_mov_b32_e32 v15, v5
	v_lshl_add_u64 v[14:15], v[12:13], 0, v[14:15]
	flat_store_dwordx4 v[14:15], v[8:11]
	ds_read_b32 v8, v25 offset:64
	ds_read_b32 v9, v25 offset:196
	ds_read_b32 v10, v25 offset:328
	ds_read_b32 v11, v25 offset:460
	ds_read_b32 v14, v25 offset:592
	ds_read_b32 v15, v25 offset:724
	ds_read_b32 v16, v25 offset:856
	ds_read_b32 v17, v25 offset:988
	s_waitcnt lgkmcnt(0)
	v_bfe_u32 v18, v8, 16, 1
	v_add3_u32 v8, v8, v18, s44
	v_bfe_u32 v18, v9, 16, 1
	v_lshrrev_b32_e32 v8, 16, v8
	v_add3_u32 v9, v9, v18, s44
	v_and_or_b32 v8, v9, s45, v8
	v_bfe_u32 v9, v10, 16, 1
	v_add3_u32 v9, v10, v9, s44
	v_bfe_u32 v10, v11, 16, 1
	v_lshrrev_b32_e32 v9, 16, v9
	v_add3_u32 v10, v11, v10, s44
	v_and_or_b32 v9, v10, s45, v9
	v_bfe_u32 v10, v14, 16, 1
	v_add3_u32 v10, v14, v10, s44
	v_bfe_u32 v11, v15, 16, 1
	v_lshrrev_b32_e32 v10, 16, v10
	v_add3_u32 v11, v15, v11, s44
	v_and_or_b32 v10, v11, s45, v10
	v_bfe_u32 v11, v16, 16, 1
	v_add3_u32 v11, v16, v11, s44
	v_bfe_u32 v14, v17, 16, 1
	v_lshrrev_b32_e32 v11, 16, v11
	v_add3_u32 v14, v17, v14, s44
	v_and_or_b32 v11, v14, s45, v11
	v_or_b32_e32 v14, s29, v27
	v_lshlrev_b32_e32 v14, 11, v14
	v_mov_b32_e32 v15, v5
	v_lshl_add_u64 v[14:15], v[12:13], 0, v[14:15]
	flat_store_dwordx4 v[14:15], v[8:11]
	ds_read_b32 v8, v25 offset:96
	ds_read_b32 v9, v25 offset:228
	ds_read_b32 v10, v25 offset:360
	ds_read_b32 v11, v25 offset:492
	ds_read_b32 v14, v25 offset:624
	ds_read_b32 v15, v25 offset:756
	ds_read_b32 v16, v25 offset:888
	ds_read_b32 v17, v25 offset:1020
	s_waitcnt lgkmcnt(0)
	v_bfe_u32 v18, v8, 16, 1
	v_add3_u32 v8, v8, v18, s44
	v_bfe_u32 v18, v9, 16, 1
	v_lshrrev_b32_e32 v8, 16, v8
	v_add3_u32 v9, v9, v18, s44
	v_and_or_b32 v8, v9, s45, v8
	v_bfe_u32 v9, v10, 16, 1
	v_add3_u32 v9, v10, v9, s44
	v_bfe_u32 v10, v11, 16, 1
	v_lshrrev_b32_e32 v9, 16, v9
	v_add3_u32 v10, v11, v10, s44
	v_and_or_b32 v9, v10, s45, v9
	v_bfe_u32 v10, v14, 16, 1
	v_add3_u32 v10, v14, v10, s44
	v_bfe_u32 v11, v15, 16, 1
	v_lshrrev_b32_e32 v10, 16, v10
	v_add3_u32 v11, v15, v11, s44
	v_and_or_b32 v10, v11, s45, v10
	v_bfe_u32 v11, v16, 16, 1
	v_add3_u32 v11, v16, v11, s44
	v_bfe_u32 v14, v17, 16, 1
	v_lshrrev_b32_e32 v11, 16, v11
	v_add3_u32 v14, v17, v14, s44
	v_and_or_b32 v11, v14, s45, v11
	v_or_b32_e32 v14, s29, v28
	v_lshlrev_b32_e32 v14, 11, v14
	v_mov_b32_e32 v15, v5
	v_lshl_add_u64 v[12:13], v[12:13], 0, v[14:15]
	flat_store_dwordx4 v[12:13], v[8:11]
	s_waitcnt lgkmcnt(0)
	s_mov_b64 s[26:27], 0

.LBB0_26:
	v_lshl_add_u64 v[40:41], v[22:23], 0, s[26:27]
	global_load_dword v100, v[40:41], off
	v_lshl_add_u64 v[40:41], v[20:21], 0, s[26:27]
	global_load_dword v101, v[40:41], off
	v_lshl_add_u64 v[40:41], v[18:19], 0, s[26:27]
	global_load_dword v102, v[40:41], off
	v_lshl_add_u64 v[40:41], v[16:17], 0, s[26:27]
	global_load_dword v103, v[40:41], off
	v_lshl_add_u64 v[40:41], v[14:15], 0, s[26:27]
	global_load_dword v104, v[40:41], off
	v_lshl_add_u64 v[40:41], v[12:13], 0, s[26:27]
	global_load_dword v105, v[40:41], off
	v_lshl_add_u64 v[40:41], v[10:11], 0, s[26:27]
	global_load_dword v106, v[40:41], off
	v_lshl_add_u64 v[40:41], v[8:9], 0, s[26:27]
	s_add_u32 s26, s26, 0x10000
	s_addc_u32 s27, s27, 0
	s_cmp_lg_u32 s26, 0x40000
	global_load_dword v107, v[40:41], off
	s_waitcnt vmcnt(0)
	ds_write_b32 v38, v100
	ds_write_b32 v38, v101 offset:264
	ds_write_b32 v38, v102 offset:528
	ds_write_b32 v38, v103 offset:792
	ds_write_b32 v38, v104 offset:1056
	ds_write_b32 v38, v105 offset:1320
	ds_write_b32 v38, v106 offset:1584
	ds_write_b32 v38, v107 offset:1848
	v_add_u32_e32 v38, 0x840, v38
	s_cbranch_scc1 .LBB0_26
	s_waitcnt lgkmcnt(0)
	ds_read_b32 v8, v25
	ds_read_b32 v9, v25 offset:132
	ds_read_b32 v10, v25 offset:264
	ds_read_b32 v11, v25 offset:396
	ds_read_b32 v14, v25 offset:528
	ds_read_b32 v15, v25 offset:660
	ds_read_b32 v16, v25 offset:792
	ds_read_b32 v17, v25 offset:924
	s_waitcnt lgkmcnt(7)
	v_bfe_u32 v18, v8, 16, 1
	v_add3_u32 v8, v8, v18, s44
	s_waitcnt lgkmcnt(6)
	v_bfe_u32 v18, v9, 16, 1
	v_lshrrev_b32_e32 v8, 16, v8
	v_add3_u32 v9, v9, v18, s44
	v_and_or_b32 v8, v9, s45, v8
	s_waitcnt lgkmcnt(5)
	v_bfe_u32 v9, v10, 16, 1
	v_add3_u32 v9, v10, v9, s44
	s_waitcnt lgkmcnt(4)
	v_bfe_u32 v10, v11, 16, 1
	v_lshrrev_b32_e32 v9, 16, v9
	v_add3_u32 v10, v11, v10, s44
	v_and_or_b32 v9, v10, s45, v9
	s_waitcnt lgkmcnt(3)
	v_bfe_u32 v10, v14, 16, 1
	v_add3_u32 v10, v14, v10, s44
	s_waitcnt lgkmcnt(2)
	v_bfe_u32 v11, v15, 16, 1
	v_lshrrev_b32_e32 v10, 16, v10
	v_add3_u32 v11, v15, v11, s44
	s_mul_i32 s27, s24, 0x280000
	v_and_or_b32 v10, v11, s45, v10
	s_waitcnt lgkmcnt(1)
	v_bfe_u32 v11, v16, 16, 1
	s_mul_hi_i32 s26, s24, 0x280000
	s_add_u32 s27, s40, s27
	v_add3_u32 v11, v16, v11, s44
	s_waitcnt lgkmcnt(0)
	v_bfe_u32 v14, v17, 16, 1
	s_addc_u32 s30, s41, s26
	s_lshl_b32 s25, s25, 1
	v_lshrrev_b32_e32 v11, 16, v11
	v_add3_u32 v14, v17, v14, s44
	s_add_u32 s26, s27, s25
	v_and_or_b32 v11, v14, s45, v11
	v_or_b32_e32 v14, s29, v24
	s_addc_u32 s27, s30, 0
	v_mul_u32_u24_e32 v14, 0x500, v14
	v_lshl_add_u64 v[12:13], s[26:27], 0, v[4:5]
	v_lshlrev_b32_e32 v14, 1, v14
	v_mov_b32_e32 v15, v5
	v_lshl_add_u64 v[14:15], v[12:13], 0, v[14:15]
	flat_store_dwordx4 v[14:15], v[8:11] offset:1536
	ds_read_b32 v8, v25 offset:32
	ds_read_b32 v9, v25 offset:164
	ds_read_b32 v10, v25 offset:296
	ds_read_b32 v11, v25 offset:428
	ds_read_b32 v14, v25 offset:560
	ds_read_b32 v15, v25 offset:692
	ds_read_b32 v16, v25 offset:824
	ds_read_b32 v17, v25 offset:956
	s_waitcnt lgkmcnt(0)
	v_bfe_u32 v18, v8, 16, 1
	v_add3_u32 v8, v8, v18, s44
	v_bfe_u32 v18, v9, 16, 1
	v_lshrrev_b32_e32 v8, 16, v8
	v_add3_u32 v9, v9, v18, s44
	v_and_or_b32 v8, v9, s45, v8
	v_bfe_u32 v9, v10, 16, 1
	v_add3_u32 v9, v10, v9, s44
	v_bfe_u32 v10, v11, 16, 1
	v_lshrrev_b32_e32 v9, 16, v9
	v_add3_u32 v10, v11, v10, s44
	v_and_or_b32 v9, v10, s45, v9
	v_bfe_u32 v10, v14, 16, 1
	v_add3_u32 v10, v14, v10, s44
	v_bfe_u32 v11, v15, 16, 1
	v_lshrrev_b32_e32 v10, 16, v10
	v_add3_u32 v11, v15, v11, s44
	v_and_or_b32 v10, v11, s45, v10
	v_bfe_u32 v11, v16, 16, 1
	v_add3_u32 v11, v16, v11, s44
	v_bfe_u32 v14, v17, 16, 1
	v_lshrrev_b32_e32 v11, 16, v11
	v_add3_u32 v14, v17, v14, s44
	v_and_or_b32 v11, v14, s45, v11
	v_or_b32_e32 v14, s29, v26
	v_mul_u32_u24_e32 v14, 0x500, v14
	v_lshlrev_b32_e32 v14, 1, v14
	v_mov_b32_e32 v15, v5
	v_lshl_add_u64 v[14:15], v[12:13], 0, v[14:15]
	flat_store_dwordx4 v[14:15], v[8:11] offset:1536
	ds_read_b32 v8, v25 offset:64
	ds_read_b32 v9, v25 offset:196
	ds_read_b32 v10, v25 offset:328
	ds_read_b32 v11, v25 offset:460
	ds_read_b32 v14, v25 offset:592
	ds_read_b32 v15, v25 offset:724
	ds_read_b32 v16, v25 offset:856
	ds_read_b32 v17, v25 offset:988
	s_waitcnt lgkmcnt(0)
	v_bfe_u32 v18, v8, 16, 1
	v_add3_u32 v8, v8, v18, s44
	v_bfe_u32 v18, v9, 16, 1
	v_lshrrev_b32_e32 v8, 16, v8
	v_add3_u32 v9, v9, v18, s44
	v_and_or_b32 v8, v9, s45, v8
	v_bfe_u32 v9, v10, 16, 1
	v_add3_u32 v9, v10, v9, s44
	v_bfe_u32 v10, v11, 16, 1
	v_lshrrev_b32_e32 v9, 16, v9
	v_add3_u32 v10, v11, v10, s44
	v_and_or_b32 v9, v10, s45, v9
	v_bfe_u32 v10, v14, 16, 1
	v_add3_u32 v10, v14, v10, s44
	v_bfe_u32 v11, v15, 16, 1
	v_lshrrev_b32_e32 v10, 16, v10
	v_add3_u32 v11, v15, v11, s44
	v_and_or_b32 v10, v11, s45, v10
	v_bfe_u32 v11, v16, 16, 1
	v_add3_u32 v11, v16, v11, s44
	v_bfe_u32 v14, v17, 16, 1
	v_lshrrev_b32_e32 v11, 16, v11
	v_add3_u32 v14, v17, v14, s44
	v_and_or_b32 v11, v14, s45, v11
	v_or_b32_e32 v14, s29, v27
	v_mul_u32_u24_e32 v14, 0x500, v14
	v_lshlrev_b32_e32 v14, 1, v14
	v_mov_b32_e32 v15, v5
	v_lshl_add_u64 v[14:15], v[12:13], 0, v[14:15]
	flat_store_dwordx4 v[14:15], v[8:11] offset:1536
	ds_read_b32 v8, v25 offset:96
	ds_read_b32 v9, v25 offset:228
	ds_read_b32 v10, v25 offset:360
	ds_read_b32 v11, v25 offset:492
	ds_read_b32 v14, v25 offset:624
	ds_read_b32 v15, v25 offset:756
	ds_read_b32 v16, v25 offset:888
	ds_read_b32 v17, v25 offset:1020
	s_waitcnt lgkmcnt(0)
	v_bfe_u32 v18, v8, 16, 1
	v_add3_u32 v8, v8, v18, s44
	v_bfe_u32 v18, v9, 16, 1
	v_lshrrev_b32_e32 v8, 16, v8
	v_add3_u32 v9, v9, v18, s44
	v_and_or_b32 v8, v9, s45, v8
	v_bfe_u32 v9, v10, 16, 1
	v_add3_u32 v9, v10, v9, s44
	v_bfe_u32 v10, v11, 16, 1
	v_lshrrev_b32_e32 v9, 16, v9
	v_add3_u32 v10, v11, v10, s44
	v_and_or_b32 v9, v10, s45, v9
	v_bfe_u32 v10, v14, 16, 1
	v_add3_u32 v10, v14, v10, s44
	v_bfe_u32 v11, v15, 16, 1
	v_lshrrev_b32_e32 v10, 16, v10
	v_add3_u32 v11, v15, v11, s44
	v_and_or_b32 v10, v11, s45, v10
	v_bfe_u32 v11, v16, 16, 1
	v_add3_u32 v11, v16, v11, s44
	v_bfe_u32 v14, v17, 16, 1
	v_lshrrev_b32_e32 v11, 16, v11
	v_add3_u32 v14, v17, v14, s44
	v_and_or_b32 v11, v14, s45, v11
	v_or_b32_e32 v14, s29, v28
	v_mul_u32_u24_e32 v14, 0x500, v14
	v_lshlrev_b32_e32 v14, 1, v14
	v_mov_b32_e32 v15, v5
	v_lshl_add_u64 v[12:13], v[12:13], 0, v[14:15]
	flat_store_dwordx4 v[12:13], v[8:11] offset:1536
	s_waitcnt lgkmcnt(0)

.LBB0_31:
	v_lshl_add_u64 v[40:41], v[22:23], 0, s[26:27]
	global_load_dword v100, v[40:41], off
	v_lshl_add_u64 v[40:41], v[20:21], 0, s[26:27]
	global_load_dword v101, v[40:41], off
	v_lshl_add_u64 v[40:41], v[18:19], 0, s[26:27]
	global_load_dword v102, v[40:41], off
	v_lshl_add_u64 v[40:41], v[16:17], 0, s[26:27]
	global_load_dword v103, v[40:41], off
	v_lshl_add_u64 v[40:41], v[14:15], 0, s[26:27]
	global_load_dword v104, v[40:41], off
	v_lshl_add_u64 v[40:41], v[12:13], 0, s[26:27]
	global_load_dword v105, v[40:41], off
	v_lshl_add_u64 v[40:41], v[10:11], 0, s[26:27]
	global_load_dword v106, v[40:41], off
	v_lshl_add_u64 v[40:41], v[8:9], 0, s[26:27]
	s_add_u32 s26, s26, 0x10000
	s_addc_u32 s27, s27, 0
	s_cmp_lg_u32 s26, 0x40000
	global_load_dword v107, v[40:41], off
	s_waitcnt vmcnt(0)
	ds_write_b32 v38, v100
	ds_write_b32 v38, v101 offset:264
	ds_write_b32 v38, v102 offset:528
	ds_write_b32 v38, v103 offset:792
	ds_write_b32 v38, v104 offset:1056
	ds_write_b32 v38, v105 offset:1320
	ds_write_b32 v38, v106 offset:1584
	ds_write_b32 v38, v107 offset:1848
	v_add_u32_e32 v38, 0x840, v38
	s_cbranch_scc1 .LBB0_31
	s_waitcnt lgkmcnt(0)
	ds_read_b32 v8, v25
	ds_read_b32 v9, v25 offset:132
	ds_read_b32 v10, v25 offset:264
	ds_read_b32 v11, v25 offset:396
	ds_read_b32 v14, v25 offset:528
	ds_read_b32 v15, v25 offset:660
	ds_read_b32 v16, v25 offset:792
	ds_read_b32 v17, v25 offset:924
	s_waitcnt lgkmcnt(7)
	v_bfe_u32 v18, v8, 16, 1
	v_add3_u32 v8, v8, v18, s44
	s_waitcnt lgkmcnt(6)
	v_bfe_u32 v18, v9, 16, 1
	v_lshrrev_b32_e32 v8, 16, v8
	v_add3_u32 v9, v9, v18, s44
	v_and_or_b32 v8, v9, s45, v8
	s_waitcnt lgkmcnt(5)
	v_bfe_u32 v9, v10, 16, 1
	v_add3_u32 v9, v10, v9, s44
	s_waitcnt lgkmcnt(4)
	v_bfe_u32 v10, v11, 16, 1
	v_lshrrev_b32_e32 v9, 16, v9
	v_add3_u32 v10, v11, v10, s44
	v_and_or_b32 v9, v10, s45, v9
	s_waitcnt lgkmcnt(3)
	v_bfe_u32 v10, v14, 16, 1
	v_add3_u32 v10, v14, v10, s44
	s_waitcnt lgkmcnt(2)
	v_bfe_u32 v11, v15, 16, 1
	s_lshl_b32 s25, s28, 5
	v_lshrrev_b32_e32 v10, 16, v10
	v_add3_u32 v11, v15, v11, s44
	s_mul_i32 s27, s24, 0x280000
	s_and_b32 s25, s25, 0x3e0
	v_and_or_b32 v10, v11, s45, v10
	s_waitcnt lgkmcnt(1)
	v_bfe_u32 v11, v16, 16, 1
	s_mul_hi_i32 s26, s24, 0x280000
	s_add_u32 s27, s40, s27
	v_add3_u32 v11, v16, v11, s44
	s_waitcnt lgkmcnt(0)
	v_bfe_u32 v14, v17, 16, 1
	s_addc_u32 s30, s41, s26
	s_lshl_b32 s26, s29, 1
	v_lshrrev_b32_e32 v11, 16, v11
	v_add3_u32 v14, v17, v14, s44
	s_add_u32 s26, s27, s26
	v_and_or_b32 v11, v14, s45, v11
	v_or_b32_e32 v14, s25, v24
	s_addc_u32 s27, s30, 0
	v_mul_u32_u24_e32 v14, 0x500, v14
	v_lshl_add_u64 v[12:13], s[26:27], 0, v[4:5]
	v_lshlrev_b32_e32 v14, 1, v14
	v_mov_b32_e32 v15, v5
	v_lshl_add_u64 v[14:15], v[12:13], 0, v[14:15]
	flat_store_dwordx4 v[14:15], v[8:11] offset:768
	ds_read_b32 v8, v25 offset:32
	ds_read_b32 v9, v25 offset:164
	ds_read_b32 v10, v25 offset:296
	ds_read_b32 v11, v25 offset:428
	ds_read_b32 v14, v25 offset:560
	ds_read_b32 v15, v25 offset:692
	ds_read_b32 v16, v25 offset:824
	ds_read_b32 v17, v25 offset:956
	s_waitcnt lgkmcnt(0)
	v_bfe_u32 v18, v8, 16, 1
	v_add3_u32 v8, v8, v18, s44
	v_bfe_u32 v18, v9, 16, 1
	v_lshrrev_b32_e32 v8, 16, v8
	v_add3_u32 v9, v9, v18, s44
	v_and_or_b32 v8, v9, s45, v8
	v_bfe_u32 v9, v10, 16, 1
	v_add3_u32 v9, v10, v9, s44
	v_bfe_u32 v10, v11, 16, 1
	v_lshrrev_b32_e32 v9, 16, v9
	v_add3_u32 v10, v11, v10, s44
	v_and_or_b32 v9, v10, s45, v9
	v_bfe_u32 v10, v14, 16, 1
	v_add3_u32 v10, v14, v10, s44
	v_bfe_u32 v11, v15, 16, 1
	v_lshrrev_b32_e32 v10, 16, v10
	v_add3_u32 v11, v15, v11, s44
	v_and_or_b32 v10, v11, s45, v10
	v_bfe_u32 v11, v16, 16, 1
	v_add3_u32 v11, v16, v11, s44
	v_bfe_u32 v14, v17, 16, 1
	v_lshrrev_b32_e32 v11, 16, v11
	v_add3_u32 v14, v17, v14, s44
	v_and_or_b32 v11, v14, s45, v11
	v_or_b32_e32 v14, s25, v26
	v_mul_u32_u24_e32 v14, 0x500, v14
	v_lshlrev_b32_e32 v14, 1, v14
	v_mov_b32_e32 v15, v5
	v_lshl_add_u64 v[14:15], v[12:13], 0, v[14:15]
	flat_store_dwordx4 v[14:15], v[8:11] offset:768
	ds_read_b32 v8, v25 offset:64
	ds_read_b32 v9, v25 offset:196
	ds_read_b32 v10, v25 offset:328
	ds_read_b32 v11, v25 offset:460
	ds_read_b32 v14, v25 offset:592
	ds_read_b32 v15, v25 offset:724
	ds_read_b32 v16, v25 offset:856
	ds_read_b32 v17, v25 offset:988
	s_waitcnt lgkmcnt(0)
	v_bfe_u32 v18, v8, 16, 1
	v_add3_u32 v8, v8, v18, s44
	v_bfe_u32 v18, v9, 16, 1
	v_lshrrev_b32_e32 v8, 16, v8
	v_add3_u32 v9, v9, v18, s44
	v_and_or_b32 v8, v9, s45, v8
	v_bfe_u32 v9, v10, 16, 1
	v_add3_u32 v9, v10, v9, s44
	v_bfe_u32 v10, v11, 16, 1
	v_lshrrev_b32_e32 v9, 16, v9
	v_add3_u32 v10, v11, v10, s44
	v_and_or_b32 v9, v10, s45, v9
	v_bfe_u32 v10, v14, 16, 1
	v_add3_u32 v10, v14, v10, s44
	v_bfe_u32 v11, v15, 16, 1
	v_lshrrev_b32_e32 v10, 16, v10
	v_add3_u32 v11, v15, v11, s44
	v_and_or_b32 v10, v11, s45, v10
	v_bfe_u32 v11, v16, 16, 1
	v_add3_u32 v11, v16, v11, s44
	v_bfe_u32 v14, v17, 16, 1
	v_lshrrev_b32_e32 v11, 16, v11
	v_add3_u32 v14, v17, v14, s44
	v_and_or_b32 v11, v14, s45, v11
	v_or_b32_e32 v14, s25, v27
	v_mul_u32_u24_e32 v14, 0x500, v14
	v_lshlrev_b32_e32 v14, 1, v14
	v_mov_b32_e32 v15, v5
	v_lshl_add_u64 v[14:15], v[12:13], 0, v[14:15]
	flat_store_dwordx4 v[14:15], v[8:11] offset:768
	ds_read_b32 v8, v25 offset:96
	ds_read_b32 v9, v25 offset:228
	ds_read_b32 v10, v25 offset:360
	ds_read_b32 v11, v25 offset:492
	ds_read_b32 v14, v25 offset:624
	ds_read_b32 v15, v25 offset:756
	ds_read_b32 v16, v25 offset:888
	ds_read_b32 v17, v25 offset:1020
	s_waitcnt lgkmcnt(0)
	v_bfe_u32 v18, v8, 16, 1
	v_add3_u32 v8, v8, v18, s44
	v_bfe_u32 v18, v9, 16, 1
	v_lshrrev_b32_e32 v8, 16, v8
	v_add3_u32 v9, v9, v18, s44
	v_and_or_b32 v8, v9, s45, v8
	v_bfe_u32 v9, v10, 16, 1
	v_add3_u32 v9, v10, v9, s44
	v_bfe_u32 v10, v11, 16, 1
	v_lshrrev_b32_e32 v9, 16, v9
	v_add3_u32 v10, v11, v10, s44
	v_and_or_b32 v9, v10, s45, v9
	v_bfe_u32 v10, v14, 16, 1
	v_add3_u32 v10, v14, v10, s44
	v_bfe_u32 v11, v15, 16, 1
	v_lshrrev_b32_e32 v10, 16, v10
	v_add3_u32 v11, v15, v11, s44
	v_and_or_b32 v10, v11, s45, v10
	v_bfe_u32 v11, v16, 16, 1
	v_add3_u32 v11, v16, v11, s44
	v_bfe_u32 v14, v17, 16, 1
	v_lshrrev_b32_e32 v11, 16, v11
	v_add3_u32 v14, v17, v14, s44
	v_and_or_b32 v11, v14, s45, v11
	v_or_b32_e32 v14, s25, v28
	v_mul_u32_u24_e32 v14, 0x500, v14
	v_lshlrev_b32_e32 v14, 1, v14
	v_mov_b32_e32 v15, v5
	v_lshl_add_u64 v[12:13], v[12:13], 0, v[14:15]
	flat_store_dwordx4 v[12:13], v[8:11] offset:768
	s_waitcnt lgkmcnt(0)

.LBB0_36:
	v_lshl_add_u64 v[40:41], v[22:23], 0, s[26:27]
	global_load_dword v100, v[40:41], off
	v_lshl_add_u64 v[40:41], v[20:21], 0, s[26:27]
	global_load_dword v101, v[40:41], off
	v_lshl_add_u64 v[40:41], v[18:19], 0, s[26:27]
	global_load_dword v102, v[40:41], off
	v_lshl_add_u64 v[40:41], v[16:17], 0, s[26:27]
	global_load_dword v103, v[40:41], off
	v_lshl_add_u64 v[40:41], v[14:15], 0, s[26:27]
	global_load_dword v104, v[40:41], off
	v_lshl_add_u64 v[40:41], v[12:13], 0, s[26:27]
	global_load_dword v105, v[40:41], off
	v_lshl_add_u64 v[40:41], v[10:11], 0, s[26:27]
	global_load_dword v106, v[40:41], off
	v_lshl_add_u64 v[40:41], v[8:9], 0, s[26:27]
	s_add_u32 s26, s26, 0x10000
	s_addc_u32 s27, s27, 0
	s_cmp_lg_u32 s26, 0x40000
	global_load_dword v107, v[40:41], off
	s_waitcnt vmcnt(0)
	ds_write_b32 v38, v100
	ds_write_b32 v38, v101 offset:264
	ds_write_b32 v38, v102 offset:528
	ds_write_b32 v38, v103 offset:792
	ds_write_b32 v38, v104 offset:1056
	ds_write_b32 v38, v105 offset:1320
	ds_write_b32 v38, v106 offset:1584
	ds_write_b32 v38, v107 offset:1848
	v_add_u32_e32 v38, 0x840, v38
	s_cbranch_scc1 .LBB0_36
	s_waitcnt lgkmcnt(0)
	ds_read_b32 v8, v25
	ds_read_b32 v9, v25 offset:132
	ds_read_b32 v10, v25 offset:264
	ds_read_b32 v11, v25 offset:396
	ds_read_b32 v14, v25 offset:528
	ds_read_b32 v15, v25 offset:660
	ds_read_b32 v16, v25 offset:792
	ds_read_b32 v17, v25 offset:924
	s_waitcnt lgkmcnt(7)
	v_bfe_u32 v18, v8, 16, 1
	v_add3_u32 v8, v8, v18, s44
	s_waitcnt lgkmcnt(6)
	v_bfe_u32 v18, v9, 16, 1
	v_lshrrev_b32_e32 v8, 16, v8
	v_add3_u32 v9, v9, v18, s44
	v_and_or_b32 v8, v9, s45, v8
	s_waitcnt lgkmcnt(5)
	v_bfe_u32 v9, v10, 16, 1
	v_add3_u32 v9, v10, v9, s44
	s_waitcnt lgkmcnt(4)
	v_bfe_u32 v10, v11, 16, 1
	v_lshrrev_b32_e32 v9, 16, v9
	v_add3_u32 v10, v11, v10, s44
	v_and_or_b32 v9, v10, s45, v9
	s_waitcnt lgkmcnt(3)
	v_bfe_u32 v10, v14, 16, 1
	v_add3_u32 v10, v14, v10, s44
	s_waitcnt lgkmcnt(2)
	v_bfe_u32 v11, v15, 16, 1
	s_lshl_b32 s25, s28, 5
	v_lshrrev_b32_e32 v10, 16, v10
	v_add3_u32 v11, v15, v11, s44
	s_mul_i32 s27, s24, 0x280000
	s_and_b32 s25, s25, 0x3e0
	v_and_or_b32 v10, v11, s45, v10
	s_waitcnt lgkmcnt(1)
	v_bfe_u32 v11, v16, 16, 1
	s_mul_hi_i32 s26, s24, 0x280000
	s_add_u32 s27, s40, s27
	v_add3_u32 v11, v16, v11, s44
	s_waitcnt lgkmcnt(0)
	v_bfe_u32 v14, v17, 16, 1
	s_addc_u32 s30, s41, s26
	s_lshl_b32 s26, s29, 1
	v_lshrrev_b32_e32 v11, 16, v11
	v_add3_u32 v14, v17, v14, s44
	s_add_u32 s26, s27, s26
	v_and_or_b32 v11, v14, s45, v11
	v_or_b32_e32 v14, s25, v24
	s_addc_u32 s27, s30, 0
	v_mul_u32_u24_e32 v14, 0x500, v14
	v_lshl_add_u64 v[12:13], s[26:27], 0, v[4:5]
	v_lshlrev_b32_e32 v14, 1, v14
	v_mov_b32_e32 v15, v5
	v_lshl_add_u64 v[14:15], v[12:13], 0, v[14:15]
	flat_store_dwordx4 v[14:15], v[8:11]
	ds_read_b32 v8, v25 offset:32
	ds_read_b32 v9, v25 offset:164
	ds_read_b32 v10, v25 offset:296
	ds_read_b32 v11, v25 offset:428
	ds_read_b32 v14, v25 offset:560
	ds_read_b32 v15, v25 offset:692
	ds_read_b32 v16, v25 offset:824
	ds_read_b32 v17, v25 offset:956
	s_waitcnt lgkmcnt(0)
	v_bfe_u32 v18, v8, 16, 1
	v_add3_u32 v8, v8, v18, s44
	v_bfe_u32 v18, v9, 16, 1
	v_lshrrev_b32_e32 v8, 16, v8
	v_add3_u32 v9, v9, v18, s44
	v_and_or_b32 v8, v9, s45, v8
	v_bfe_u32 v9, v10, 16, 1
	v_add3_u32 v9, v10, v9, s44
	v_bfe_u32 v10, v11, 16, 1
	v_lshrrev_b32_e32 v9, 16, v9
	v_add3_u32 v10, v11, v10, s44
	v_and_or_b32 v9, v10, s45, v9
	v_bfe_u32 v10, v14, 16, 1
	v_add3_u32 v10, v14, v10, s44
	v_bfe_u32 v11, v15, 16, 1
	v_lshrrev_b32_e32 v10, 16, v10
	v_add3_u32 v11, v15, v11, s44
	v_and_or_b32 v10, v11, s45, v10
	v_bfe_u32 v11, v16, 16, 1
	v_add3_u32 v11, v16, v11, s44
	v_bfe_u32 v14, v17, 16, 1
	v_lshrrev_b32_e32 v11, 16, v11
	v_add3_u32 v14, v17, v14, s44
	v_and_or_b32 v11, v14, s45, v11
	v_or_b32_e32 v14, s25, v26
	v_mul_u32_u24_e32 v14, 0x500, v14
	v_lshlrev_b32_e32 v14, 1, v14
	v_mov_b32_e32 v15, v5
	v_lshl_add_u64 v[14:15], v[12:13], 0, v[14:15]
	flat_store_dwordx4 v[14:15], v[8:11]
	ds_read_b32 v8, v25 offset:64
	ds_read_b32 v9, v25 offset:196
	ds_read_b32 v10, v25 offset:328
	ds_read_b32 v11, v25 offset:460
	ds_read_b32 v14, v25 offset:592
	ds_read_b32 v15, v25 offset:724
	ds_read_b32 v16, v25 offset:856
	ds_read_b32 v17, v25 offset:988
	s_waitcnt lgkmcnt(0)
	v_bfe_u32 v18, v8, 16, 1
	v_add3_u32 v8, v8, v18, s44
	v_bfe_u32 v18, v9, 16, 1
	v_lshrrev_b32_e32 v8, 16, v8
	v_add3_u32 v9, v9, v18, s44
	v_and_or_b32 v8, v9, s45, v8
	v_bfe_u32 v9, v10, 16, 1
	v_add3_u32 v9, v10, v9, s44
	v_bfe_u32 v10, v11, 16, 1
	v_lshrrev_b32_e32 v9, 16, v9
	v_add3_u32 v10, v11, v10, s44
	v_and_or_b32 v9, v10, s45, v9
	v_bfe_u32 v10, v14, 16, 1
	v_add3_u32 v10, v14, v10, s44
	v_bfe_u32 v11, v15, 16, 1
	v_lshrrev_b32_e32 v10, 16, v10
	v_add3_u32 v11, v15, v11, s44
	v_and_or_b32 v10, v11, s45, v10
	v_bfe_u32 v11, v16, 16, 1
	v_add3_u32 v11, v16, v11, s44
	v_bfe_u32 v14, v17, 16, 1
	v_lshrrev_b32_e32 v11, 16, v11
	v_add3_u32 v14, v17, v14, s44
	v_and_or_b32 v11, v14, s45, v11
	v_or_b32_e32 v14, s25, v27
	v_mul_u32_u24_e32 v14, 0x500, v14
	v_lshlrev_b32_e32 v14, 1, v14
	v_mov_b32_e32 v15, v5
	v_lshl_add_u64 v[14:15], v[12:13], 0, v[14:15]
	flat_store_dwordx4 v[14:15], v[8:11]
	ds_read_b32 v8, v25 offset:96
	ds_read_b32 v9, v25 offset:228
	ds_read_b32 v10, v25 offset:360
	ds_read_b32 v11, v25 offset:492
	ds_read_b32 v14, v25 offset:624
	ds_read_b32 v15, v25 offset:756
	ds_read_b32 v16, v25 offset:888
	ds_read_b32 v17, v25 offset:1020
	s_waitcnt lgkmcnt(0)
	v_bfe_u32 v18, v8, 16, 1
	v_add3_u32 v8, v8, v18, s44
	v_bfe_u32 v18, v9, 16, 1
	v_lshrrev_b32_e32 v8, 16, v8
	v_add3_u32 v9, v9, v18, s44
	v_and_or_b32 v8, v9, s45, v8
	v_bfe_u32 v9, v10, 16, 1
	v_add3_u32 v9, v10, v9, s44
	v_bfe_u32 v10, v11, 16, 1
	v_lshrrev_b32_e32 v9, 16, v9
	v_add3_u32 v10, v11, v10, s44
	v_and_or_b32 v9, v10, s45, v9
	v_bfe_u32 v10, v14, 16, 1
	v_add3_u32 v10, v14, v10, s44
	v_bfe_u32 v11, v15, 16, 1
	v_lshrrev_b32_e32 v10, 16, v10
	v_add3_u32 v11, v15, v11, s44
	v_and_or_b32 v10, v11, s45, v10
	v_bfe_u32 v11, v16, 16, 1
	v_add3_u32 v11, v16, v11, s44
	v_bfe_u32 v14, v17, 16, 1
	v_lshrrev_b32_e32 v11, 16, v11
	v_add3_u32 v14, v17, v14, s44
	v_and_or_b32 v11, v14, s45, v11
	v_or_b32_e32 v14, s25, v28
	v_mul_u32_u24_e32 v14, 0x500, v14
	v_lshlrev_b32_e32 v14, 1, v14
	v_mov_b32_e32 v15, v5
	v_lshl_add_u64 v[12:13], v[12:13], 0, v[14:15]
	flat_store_dwordx4 v[12:13], v[8:11]
	s_waitcnt lgkmcnt(0)

.LBB0_41:
	v_lshl_add_u64 v[40:41], v[22:23], 0, s[26:27]
	global_load_dword v100, v[40:41], off
	v_lshl_add_u64 v[40:41], v[20:21], 0, s[26:27]
	global_load_dword v101, v[40:41], off
	v_lshl_add_u64 v[40:41], v[18:19], 0, s[26:27]
	global_load_dword v102, v[40:41], off
	v_lshl_add_u64 v[40:41], v[16:17], 0, s[26:27]
	global_load_dword v103, v[40:41], off
	v_lshl_add_u64 v[40:41], v[14:15], 0, s[26:27]
	global_load_dword v104, v[40:41], off
	v_lshl_add_u64 v[40:41], v[12:13], 0, s[26:27]
	global_load_dword v105, v[40:41], off
	v_lshl_add_u64 v[40:41], v[10:11], 0, s[26:27]
	global_load_dword v106, v[40:41], off
	v_lshl_add_u64 v[40:41], v[8:9], 0, s[26:27]
	s_add_u32 s26, s26, 0x30000
	s_addc_u32 s27, s27, 0
	s_cmp_lg_u32 s26, 0xc0000
	global_load_dword v107, v[40:41], off
	s_waitcnt vmcnt(0)
	ds_write_b32 v38, v100
	ds_write_b32 v38, v101 offset:264
	ds_write_b32 v38, v102 offset:528
	ds_write_b32 v38, v103 offset:792
	ds_write_b32 v38, v104 offset:1056
	ds_write_b32 v38, v105 offset:1320
	ds_write_b32 v38, v106 offset:1584
	ds_write_b32 v38, v107 offset:1848
	v_add_u32_e32 v38, 0x840, v38
	s_cbranch_scc1 .LBB0_41
	s_waitcnt lgkmcnt(0)
	ds_read_b32 v8, v25
	ds_read_b32 v9, v25 offset:132
	ds_read_b32 v10, v25 offset:264
	ds_read_b32 v11, v25 offset:396
	ds_read_b32 v14, v25 offset:528
	ds_read_b32 v15, v25 offset:660
	ds_read_b32 v16, v25 offset:792
	ds_read_b32 v17, v25 offset:924
	s_waitcnt lgkmcnt(7)
	v_bfe_u32 v18, v8, 16, 1
	v_add3_u32 v8, v8, v18, s44
	s_waitcnt lgkmcnt(6)
	v_bfe_u32 v18, v9, 16, 1
	v_lshrrev_b32_e32 v8, 16, v8
	v_add3_u32 v9, v9, v18, s44
	v_and_or_b32 v8, v9, s45, v8
	s_waitcnt lgkmcnt(5)
	v_bfe_u32 v9, v10, 16, 1
	v_add3_u32 v9, v10, v9, s44
	s_waitcnt lgkmcnt(4)
	v_bfe_u32 v10, v11, 16, 1
	v_lshrrev_b32_e32 v9, 16, v9
	v_add3_u32 v10, v11, v10, s44
	v_and_or_b32 v9, v10, s45, v9
	s_waitcnt lgkmcnt(3)
	v_bfe_u32 v10, v14, 16, 1
	s_mul_i32 s27, s24, 0x1380000
	v_add3_u32 v10, v14, v10, s44
	s_waitcnt lgkmcnt(2)
	v_bfe_u32 v11, v15, 16, 1
	s_mul_hi_i32 s26, s24, 0x1380000
	s_add_u32 s27, s38, s27
	v_lshrrev_b32_e32 v10, 16, v10
	v_add3_u32 v11, v15, v11, s44
	s_addc_u32 s30, s39, s26
	s_addk_i32 s25, 0x1b00
	s_and_b32 s26, 0xffff, s29
	v_and_or_b32 v10, v11, s45, v10
	s_waitcnt lgkmcnt(1)
	v_bfe_u32 v11, v16, 16, 1
	s_and_b32 s25, s25, 0xffff
	s_lshl_b32 s26, s26, 1
	v_add3_u32 v11, v16, v11, s44
	s_waitcnt lgkmcnt(0)
	v_bfe_u32 v14, v17, 16, 1
	s_add_u32 s26, s27, s26
	v_lshrrev_b32_e32 v11, 16, v11
	v_add3_u32 v14, v17, v14, s44
	s_addc_u32 s27, s30, 0
	v_and_or_b32 v11, v14, s45, v11
	v_or_b32_e32 v14, s25, v24
	v_lshl_add_u64 v[12:13], s[26:27], 0, v[4:5]
	v_lshlrev_b32_e32 v14, 11, v14
	v_mov_b32_e32 v15, v5
	v_lshl_add_u64 v[14:15], v[12:13], 0, v[14:15]
	flat_store_dwordx4 v[14:15], v[8:11]
	ds_read_b32 v8, v25 offset:32
	ds_read_b32 v9, v25 offset:164
	ds_read_b32 v10, v25 offset:296
	ds_read_b32 v11, v25 offset:428
	ds_read_b32 v14, v25 offset:560
	ds_read_b32 v15, v25 offset:692
	ds_read_b32 v16, v25 offset:824
	ds_read_b32 v17, v25 offset:956
	s_waitcnt lgkmcnt(0)
	v_bfe_u32 v18, v8, 16, 1
	v_add3_u32 v8, v8, v18, s44
	v_bfe_u32 v18, v9, 16, 1
	v_lshrrev_b32_e32 v8, 16, v8
	v_add3_u32 v9, v9, v18, s44
	v_and_or_b32 v8, v9, s45, v8
	v_bfe_u32 v9, v10, 16, 1
	v_add3_u32 v9, v10, v9, s44
	v_bfe_u32 v10, v11, 16, 1
	v_lshrrev_b32_e32 v9, 16, v9
	v_add3_u32 v10, v11, v10, s44
	v_and_or_b32 v9, v10, s45, v9
	v_bfe_u32 v10, v14, 16, 1
	v_add3_u32 v10, v14, v10, s44
	v_bfe_u32 v11, v15, 16, 1
	v_lshrrev_b32_e32 v10, 16, v10
	v_add3_u32 v11, v15, v11, s44
	v_and_or_b32 v10, v11, s45, v10
	v_bfe_u32 v11, v16, 16, 1
	v_add3_u32 v11, v16, v11, s44
	v_bfe_u32 v14, v17, 16, 1
	v_lshrrev_b32_e32 v11, 16, v11
	v_add3_u32 v14, v17, v14, s44
	v_and_or_b32 v11, v14, s45, v11
	v_or_b32_e32 v14, s25, v26
	v_lshlrev_b32_e32 v14, 11, v14
	v_mov_b32_e32 v15, v5
	v_lshl_add_u64 v[14:15], v[12:13], 0, v[14:15]
	flat_store_dwordx4 v[14:15], v[8:11]
	ds_read_b32 v8, v25 offset:64
	ds_read_b32 v9, v25 offset:196
	ds_read_b32 v10, v25 offset:328
	ds_read_b32 v11, v25 offset:460
	ds_read_b32 v14, v25 offset:592
	ds_read_b32 v15, v25 offset:724
	ds_read_b32 v16, v25 offset:856
	ds_read_b32 v17, v25 offset:988
	s_waitcnt lgkmcnt(0)
	v_bfe_u32 v18, v8, 16, 1
	v_add3_u32 v8, v8, v18, s44
	v_bfe_u32 v18, v9, 16, 1
	v_lshrrev_b32_e32 v8, 16, v8
	v_add3_u32 v9, v9, v18, s44
	v_and_or_b32 v8, v9, s45, v8
	v_bfe_u32 v9, v10, 16, 1
	v_add3_u32 v9, v10, v9, s44
	v_bfe_u32 v10, v11, 16, 1
	v_lshrrev_b32_e32 v9, 16, v9
	v_add3_u32 v10, v11, v10, s44
	v_and_or_b32 v9, v10, s45, v9
	v_bfe_u32 v10, v14, 16, 1
	v_add3_u32 v10, v14, v10, s44
	v_bfe_u32 v11, v15, 16, 1
	v_lshrrev_b32_e32 v10, 16, v10
	v_add3_u32 v11, v15, v11, s44
	v_and_or_b32 v10, v11, s45, v10
	v_bfe_u32 v11, v16, 16, 1
	v_add3_u32 v11, v16, v11, s44
	v_bfe_u32 v14, v17, 16, 1
	v_lshrrev_b32_e32 v11, 16, v11
	v_add3_u32 v14, v17, v14, s44
	v_and_or_b32 v11, v14, s45, v11
	v_or_b32_e32 v14, s25, v27
	v_lshlrev_b32_e32 v14, 11, v14
	v_mov_b32_e32 v15, v5
	v_lshl_add_u64 v[14:15], v[12:13], 0, v[14:15]
	flat_store_dwordx4 v[14:15], v[8:11]
	ds_read_b32 v8, v25 offset:96
	ds_read_b32 v9, v25 offset:228
	ds_read_b32 v10, v25 offset:360
	ds_read_b32 v11, v25 offset:492
	ds_read_b32 v14, v25 offset:624
	ds_read_b32 v15, v25 offset:756
	ds_read_b32 v16, v25 offset:888
	ds_read_b32 v17, v25 offset:1020
	s_waitcnt lgkmcnt(0)
	v_bfe_u32 v18, v8, 16, 1
	v_add3_u32 v8, v8, v18, s44
	v_bfe_u32 v18, v9, 16, 1
	v_lshrrev_b32_e32 v8, 16, v8
	v_add3_u32 v9, v9, v18, s44
	v_and_or_b32 v8, v9, s45, v8
	v_bfe_u32 v9, v10, 16, 1
	v_add3_u32 v9, v10, v9, s44
	v_bfe_u32 v10, v11, 16, 1
	v_lshrrev_b32_e32 v9, 16, v9
	v_add3_u32 v10, v11, v10, s44
	v_and_or_b32 v9, v10, s45, v9
	v_bfe_u32 v10, v14, 16, 1
	v_add3_u32 v10, v14, v10, s44
	v_bfe_u32 v11, v15, 16, 1
	v_lshrrev_b32_e32 v10, 16, v10
	v_add3_u32 v11, v15, v11, s44
	v_and_or_b32 v10, v11, s45, v10
	v_bfe_u32 v11, v16, 16, 1
	v_add3_u32 v11, v16, v11, s44
	v_bfe_u32 v14, v17, 16, 1
	v_lshrrev_b32_e32 v11, 16, v11
	v_add3_u32 v14, v17, v14, s44
	v_and_or_b32 v11, v14, s45, v11
	v_or_b32_e32 v14, s25, v28
	v_lshlrev_b32_e32 v14, 11, v14
	v_mov_b32_e32 v15, v5
	v_lshl_add_u64 v[12:13], v[12:13], 0, v[14:15]
	flat_store_dwordx4 v[12:13], v[8:11]
	s_waitcnt lgkmcnt(0)

.LBB0_45:
	v_lshl_add_u64 v[40:41], v[22:23], 0, s[30:31]
	global_load_dword v100, v[40:41], off
	v_lshl_add_u64 v[40:41], v[20:21], 0, s[30:31]
	global_load_dword v101, v[40:41], off
	v_lshl_add_u64 v[40:41], v[18:19], 0, s[30:31]
	global_load_dword v102, v[40:41], off
	v_lshl_add_u64 v[40:41], v[16:17], 0, s[30:31]
	global_load_dword v103, v[40:41], off
	v_lshl_add_u64 v[40:41], v[14:15], 0, s[30:31]
	global_load_dword v104, v[40:41], off
	v_lshl_add_u64 v[40:41], v[12:13], 0, s[30:31]
	global_load_dword v105, v[40:41], off
	v_lshl_add_u64 v[40:41], v[10:11], 0, s[30:31]
	global_load_dword v106, v[40:41], off
	v_lshl_add_u64 v[40:41], v[8:9], 0, s[30:31]
	s_add_u32 s30, s30, 0x6c000
	s_addc_u32 s31, s31, 0
	s_cmp_lg_u32 s30, 0x1b0000
	global_load_dword v107, v[40:41], off
	s_waitcnt vmcnt(0)
	ds_write_b32 v38, v100
	ds_write_b32 v38, v101 offset:264
	ds_write_b32 v38, v102 offset:528
	ds_write_b32 v38, v103 offset:792
	ds_write_b32 v38, v104 offset:1056
	ds_write_b32 v38, v105 offset:1320
	ds_write_b32 v38, v106 offset:1584
	ds_write_b32 v38, v107 offset:1848
	v_add_u32_e32 v38, 0x840, v38
	s_cbranch_scc1 .LBB0_45
	s_waitcnt lgkmcnt(0)
	ds_read_b32 v8, v25
	ds_read_b32 v9, v25 offset:132
	ds_read_b32 v10, v25 offset:264
	ds_read_b32 v11, v25 offset:396
	ds_read_b32 v14, v25 offset:528
	ds_read_b32 v15, v25 offset:660
	ds_read_b32 v16, v25 offset:792
	ds_read_b32 v17, v25 offset:924
	s_waitcnt lgkmcnt(7)
	v_bfe_u32 v18, v8, 16, 1
	v_add3_u32 v8, v8, v18, s44
	s_waitcnt lgkmcnt(6)
	v_bfe_u32 v18, v9, 16, 1
	v_lshrrev_b32_e32 v8, 16, v8
	v_add3_u32 v9, v9, v18, s44
	v_and_or_b32 v8, v9, s45, v8
	s_waitcnt lgkmcnt(5)
	v_bfe_u32 v9, v10, 16, 1
	v_add3_u32 v9, v10, v9, s44
	s_waitcnt lgkmcnt(4)
	v_bfe_u32 v10, v11, 16, 1
	v_lshrrev_b32_e32 v9, 16, v9
	v_add3_u32 v10, v11, v10, s44
	v_and_or_b32 v9, v10, s45, v9
	s_waitcnt lgkmcnt(3)
	v_bfe_u32 v10, v14, 16, 1
	v_add3_u32 v10, v14, v10, s44
	s_waitcnt lgkmcnt(2)
	v_bfe_u32 v11, v15, 16, 1
	s_mul_hi_i32 s25, s24, 0x1380000
	s_mul_i32 s24, s24, 0x1380000
	v_lshrrev_b32_e32 v10, 16, v10
	v_add3_u32 v11, v15, v11, s44
	s_add_u32 s27, s38, s24
	v_and_or_b32 v10, v11, s45, v10
	s_waitcnt lgkmcnt(1)
	v_bfe_u32 v11, v16, 16, 1
	s_addc_u32 s30, s39, s25
	s_ashr_i32 s29, s28, 31
	v_add3_u32 v11, v16, v11, s44
	s_waitcnt lgkmcnt(0)
	v_bfe_u32 v14, v17, 16, 1
	s_lshl_b64 s[24:25], s[28:29], 1
	v_lshrrev_b32_e32 v11, 16, v11
	v_add3_u32 v14, v17, v14, s44
	s_add_u32 s24, s27, s24
	v_and_or_b32 v11, v14, s45, v11
	v_or_b32_e32 v14, s26, v24
	s_addc_u32 s25, s30, s25
	v_ashrrev_i32_e32 v15, 31, v14
	v_lshl_add_u64 v[12:13], s[24:25], 0, v[4:5]
	v_lshlrev_b64 v[14:15], 11, v[14:15]
	v_lshl_add_u64 v[14:15], v[12:13], 0, v[14:15]
	flat_store_dwordx4 v[14:15], v[8:11]
	ds_read_b32 v8, v25 offset:32
	ds_read_b32 v9, v25 offset:164
	ds_read_b32 v10, v25 offset:296
	ds_read_b32 v11, v25 offset:428
	ds_read_b32 v14, v25 offset:560
	ds_read_b32 v15, v25 offset:692
	ds_read_b32 v16, v25 offset:824
	ds_read_b32 v17, v25 offset:956
	s_waitcnt lgkmcnt(0)
	v_bfe_u32 v18, v8, 16, 1
	v_add3_u32 v8, v8, v18, s44
	v_bfe_u32 v18, v9, 16, 1
	v_lshrrev_b32_e32 v8, 16, v8
	v_add3_u32 v9, v9, v18, s44
	v_and_or_b32 v8, v9, s45, v8
	v_bfe_u32 v9, v10, 16, 1
	v_add3_u32 v9, v10, v9, s44
	v_bfe_u32 v10, v11, 16, 1
	v_lshrrev_b32_e32 v9, 16, v9
	v_add3_u32 v10, v11, v10, s44
	v_and_or_b32 v9, v10, s45, v9
	v_bfe_u32 v10, v14, 16, 1
	v_add3_u32 v10, v14, v10, s44
	v_bfe_u32 v11, v15, 16, 1
	v_lshrrev_b32_e32 v10, 16, v10
	v_add3_u32 v11, v15, v11, s44
	v_and_or_b32 v10, v11, s45, v10
	v_bfe_u32 v11, v16, 16, 1
	v_add3_u32 v11, v16, v11, s44
	v_bfe_u32 v14, v17, 16, 1
	v_lshrrev_b32_e32 v11, 16, v11
	v_add3_u32 v14, v17, v14, s44
	v_and_or_b32 v11, v14, s45, v11
	v_or_b32_e32 v14, s26, v26
	v_ashrrev_i32_e32 v15, 31, v14
	v_lshlrev_b64 v[14:15], 11, v[14:15]
	v_lshl_add_u64 v[14:15], v[12:13], 0, v[14:15]
	flat_store_dwordx4 v[14:15], v[8:11]
	ds_read_b32 v8, v25 offset:64
	ds_read_b32 v9, v25 offset:196
	ds_read_b32 v10, v25 offset:328
	ds_read_b32 v11, v25 offset:460
	ds_read_b32 v14, v25 offset:592
	ds_read_b32 v15, v25 offset:724
	ds_read_b32 v16, v25 offset:856
	ds_read_b32 v17, v25 offset:988
	s_waitcnt lgkmcnt(0)
	v_bfe_u32 v18, v8, 16, 1
	v_add3_u32 v8, v8, v18, s44
	v_bfe_u32 v18, v9, 16, 1
	v_lshrrev_b32_e32 v8, 16, v8
	v_add3_u32 v9, v9, v18, s44
	v_and_or_b32 v8, v9, s45, v8
	v_bfe_u32 v9, v10, 16, 1
	v_add3_u32 v9, v10, v9, s44
	v_bfe_u32 v10, v11, 16, 1
	v_lshrrev_b32_e32 v9, 16, v9
	v_add3_u32 v10, v11, v10, s44
	v_and_or_b32 v9, v10, s45, v9
	v_bfe_u32 v10, v14, 16, 1
	v_add3_u32 v10, v14, v10, s44
	v_bfe_u32 v11, v15, 16, 1
	v_lshrrev_b32_e32 v10, 16, v10
	v_add3_u32 v11, v15, v11, s44
	v_and_or_b32 v10, v11, s45, v10
	v_bfe_u32 v11, v16, 16, 1
	v_add3_u32 v11, v16, v11, s44
	v_bfe_u32 v14, v17, 16, 1
	v_lshrrev_b32_e32 v11, 16, v11
	v_add3_u32 v14, v17, v14, s44
	v_and_or_b32 v11, v14, s45, v11
	v_or_b32_e32 v14, s26, v27
	v_ashrrev_i32_e32 v15, 31, v14
	v_lshlrev_b64 v[14:15], 11, v[14:15]
	v_lshl_add_u64 v[14:15], v[12:13], 0, v[14:15]
	flat_store_dwordx4 v[14:15], v[8:11]
	ds_read_b32 v8, v25 offset:96
	ds_read_b32 v9, v25 offset:228
	ds_read_b32 v10, v25 offset:360
	ds_read_b32 v11, v25 offset:492
	ds_read_b32 v14, v25 offset:624
	ds_read_b32 v15, v25 offset:756
	ds_read_b32 v16, v25 offset:888
	ds_read_b32 v17, v25 offset:1020
	s_waitcnt lgkmcnt(0)
	v_bfe_u32 v18, v8, 16, 1
	v_add3_u32 v8, v8, v18, s44
	v_bfe_u32 v18, v9, 16, 1
	v_lshrrev_b32_e32 v8, 16, v8
	v_add3_u32 v9, v9, v18, s44
	v_and_or_b32 v8, v9, s45, v8
	v_bfe_u32 v9, v10, 16, 1
	v_add3_u32 v9, v10, v9, s44
	v_bfe_u32 v10, v11, 16, 1
	v_lshrrev_b32_e32 v9, 16, v9
	v_add3_u32 v10, v11, v10, s44
	v_and_or_b32 v9, v10, s45, v9
	v_bfe_u32 v10, v14, 16, 1
	v_add3_u32 v10, v14, v10, s44
	v_bfe_u32 v11, v15, 16, 1
	v_lshrrev_b32_e32 v10, 16, v10
	v_add3_u32 v11, v15, v11, s44
	v_and_or_b32 v10, v11, s45, v10
	v_bfe_u32 v11, v16, 16, 1
	v_add3_u32 v11, v16, v11, s44
	v_bfe_u32 v14, v17, 16, 1
	v_lshrrev_b32_e32 v11, 16, v11
	v_add3_u32 v14, v17, v14, s44
	v_and_or_b32 v11, v14, s45, v11
	v_or_b32_e32 v14, s26, v28
	v_ashrrev_i32_e32 v15, 31, v14
	v_lshlrev_b64 v[14:15], 11, v[14:15]
	v_lshl_add_u64 v[12:13], v[12:13], 0, v[14:15]
	flat_store_dwordx4 v[12:13], v[8:11]
	s_waitcnt lgkmcnt(0)
	s_branch .LBB0_14
